# speedup vs baseline: 1.0029x; 1.0029x over previous
; #define PH(k) for (int rep_ = 0; rep_ < 1 + ((REPMASK >> (k)) & 1); ++rep_) if (ONLY < 0 || ONLY == (k))
; __device__ __forceinline__ void attn_block(const Params& p, int bt_raw, char* smem) {
;   const int tid = opaque_tid(), lane = tid & 63, wid = tid >> 6, fr = lane & 15, fq = lane >> 4;
;   const int bt = (bt_raw & ~31) | (((bt_raw & 31) + 8 * (bt_raw >> 8)) & 31);
;   const int b = bt >> 6, kvh = (bt >> 5) & 1, t0b = (bt & 31) * 64, t0 = t0b + wid * 8;
;   u16* Tb = (u16*)(smem + wid * 8704);
;   float* imp = (float*)(smem + 69632 + wid * 1088);
;   unsigned* msk = (unsigned*)(smem + 69632 + wid * 1088 + 1024);
;   unsigned* blkU = (unsigned*)(smem + 78336);
;   u16* KLb = (u16*)(smem + 78400);
;   u16* VLb = (u16*)(smem + 113216);
;   const u16* Z = p.Z;
;   const int hq = kvh * 4 + (fr >> 2);
;   const float slope2 = exp2f(-(float)(hq + 1)) * 1.4426950408889634f;
; __global__ void __launch_bounds__(512) mega(Params p) {
;     ...
;   PH(5) for (int bt = blockIdx.x; bt < 1024; bt += gridDim.x) attn_block(p, bt, smem);
.LBB0_258:
	s_or_b64 exec, exec, s[0:1]
	v_readlane_b32 s2, v248, 62
	v_readlane_b32 s3, v248, 63
	s_andn2_b64 vcc, exec, s[2:3]
	s_nop 0
	v_cndmask_b32_e64 v0, 0, 1, s[2:3]
	v_cmp_ne_u32_e64 s[0:1], 1, v0
	s_barrier
	s_cbranch_vccnz .LBB0_388
	v_readfirstlane_b32 s32, v194
	s_nop 3
	s_lshr_b32 s32, s32, 8
	s_cmp_eq_u32 s32, 1
	s_cbranch_scc0 .Lprio3_skip
	s_setprio 1
.Lprio3_skip:
	s_lshl_b32 s33, s60, 6
	s_lshl_b32 s34, s61, 6
	s_add_u32 s16, s88, 0xffa1b000
	s_addc_u32 s17, s89, -1
	v_mov_b32_e32 v145, 0
	s_movk_i32 s35, 0x3600
	v_mov_b64_e32 v[146:147], s[88:89]
	s_mov_b64 s[18:19], 0x1800
	s_movk_i32 s36, 0x1000
	s_mov_b32 s21, 0
	s_mov_b64 s[22:23], 0x3400
	s_movk_i32 s37, 0x3000
	s_movk_i32 s38, 0x2000
	s_add_i32 s39, 0, 0x11000
	s_mov_b64 s[24:25], 0x2000
	s_add_i32 s40, 0, 0x13210
	s_add_i32 s41, 0, 0x13240
	s_movk_i32 s42, 0x200
	s_mov_b32 s43, 0x6f000
	s_mov_b64 s[26:27], 0xd8000
	v_mov_b32_e32 v196, 0x42800000
	v_not_b32_e32 v197, 63
	v_mbcnt_hi_u32_b32 v198, -1, v195
	s_mov_b32 s44, s60
	s_branch .LBB0_262

; __device__ __forceinline__ unsigned xb_add(unsigned* p, unsigned v) { return __hip_atomic_fetch_add(p, v, __ATOMIC_RELAXED, __HIP_MEMORY_SCOPE_AGENT); }
; __device__ __forceinline__ void xcd_barrier(const XcdBarrier& b) {
;   asm volatile("s_waitcnt vmcnt(0)" ::: "memory");
;   __syncthreads();
;   if (threadIdx.x == 0) {
;     unsigned* bar = b.bar;
;     __builtin_amdgcn_s_waitcnt(0);
;     const unsigned old = xb_add(&bar[XB_XSUB(b.x)], 1u);
;     const unsigned gen = old / b.nloc;
;     if (old + 1u == (gen + 1u) * b.nloc) {
;       __builtin_amdgcn_fence(__ATOMIC_RELEASE, "agent");
;       asm volatile("s_waitcnt vmcnt(0)" ::: "memory");
;       const unsigned og = xb_add(&bar[XB_TOP], 1u);
.LBB0_388:
	s_setprio 0
	s_waitcnt vmcnt(0)
	s_barrier
	s_mov_b64 s[2:3], exec
	v_readlane_b32 s4, v248, 8
	v_readlane_b32 s5, v248, 9
	s_and_b64 s[4:5], s[2:3], s[4:5]
	s_mov_b64 exec, s[4:5]
	s_cbranch_execz .LBB0_425
	s_mov_b64 s[4:5], exec
	v_mbcnt_lo_u32_b32 v0, s4, 0
	v_readlane_b32 s6, v248, 26
	v_mbcnt_hi_u32_b32 v0, s5, v0
	s_lshl_b32 s22, s6, 6
	s_mov_b32 s9, 0
	v_cmp_eq_u32_e32 vcc, 0, v0
	s_waitcnt vmcnt(0) expcnt(0) lgkmcnt(0)
	s_and_saveexec_b64 s[6:7], vcc
	s_cbranch_execz .LBB0_391
	s_add_i32 s8, s22, 0x500
	s_lshl_b64 s[8:9], s[8:9], 2
	v_readlane_b32 s10, v248, 6
	v_readlane_b32 s11, v248, 7
	s_add_u32 s8, s10, s8
	s_addc_u32 s9, s11, s9
	s_bcnt1_i32_b64 s4, s[4:5]
	v_mov_b32_e32 v1, 0
	v_mov_b32_e32 v2, s4
	global_atomic_add v1, v1, v2, s[8:9] sc0

; #define PH(k) for (int rep_ = 0; rep_ < 1 + ((REPMASK >> (k)) & 1); ++rep_) if (ONLY < 0 || ONLY == (k))
; __device__ __forceinline__ void hgrn_block(const Params& p, int bh, char* smem) {
;   const int tid = opaque_tid(), lane = tid & 63, wid = tid >> 6, fr = lane & 15, fq = lane >> 4;
;   const int b = bh >> 4, h = bh & 15;
;   u16* QA = (u16*)smem;
;   u16* KB = QA + 64 * 136;
;   u16* QIN = KB + 64 * 136;
;   u16* KSTT = QIN + 64 * 136;
;   u16* VT = KSTT + 128 * 72;
;   u16* AT = VT + 128 * 72;
;   u16* STT = AT + 64 * 72;
;   float* dec = (float*)(STT + 128 * 136);
;   float* gsum = dec + 128;
;   float* ssq = gsum + 8 * 128;
;   for (int i = tid; i < 128 * 136 / 2; i += 512) ((unsigned*)STT)[i] = 0u;
; __global__ void __launch_bounds__(512) mega(Params p) {
;     ...
;   PH(9) for (int bh = blockIdx.x; bh < 256; bh += gridDim.x) hgrn_block(p, bh, smem);
.LBB0_591:
	s_or_b64 exec, exec, s[2:3]
	s_cmpk_gt_i32 s60, 0xff
	s_barrier
	s_cbranch_scc1 .LBB0_609
	v_readfirstlane_b32 s32, v194
	s_nop 3
	s_lshr_b32 s32, s32, 8
	s_cmp_eq_u32 s32, 1
	s_cbranch_scc0 .Lprio7_skip
	s_setprio 1
.Lprio7_skip:
	v_readlane_b32 s76, v247, 0
	v_readlane_b32 s2, v248, 61
	s_lshl_b32 s33, s76, 7
	s_lshl_b32 s54, s2, 7
	v_mbcnt_hi_u32_b32 v106, -1, v195
	s_add_u32 s2, s88, 0x3040
	v_and_b32_e32 v0, 64, v106
	s_addc_u32 s3, s89, 0
	s_mov_b32 s47, 0
	s_add_i32 s55, 0, 0x18000
	v_mov_b32_e32 v51, 0
	s_movk_i32 s56, 0x2000
	s_mov_b32 s57, 0xd000
	s_mov_b32 s58, 0xe000
	s_mov_b32 s59, 0x11000
	s_mov_b32 s60, 0x12000
	s_mov_b32 s61, 0x15000
	s_mov_b32 s62, 0x16000
	s_mov_b32 s63, 0x19000
	s_mov_b32 s64, 0x1a000
	s_mov_b32 s65, 0x1d000
	s_mov_b32 s66, 0x1e000
	s_add_i32 s67, 0, 0x20a00
	s_add_i32 s68, 0, 0x11400
	s_movk_i32 s69, 0x90
	s_add_i32 s70, 0, 0x15c00
	s_movk_i32 s71, 0x110
	v_xor_b32_e32 v107, 16, v106
	v_add_u32_e32 v108, 64, v0
	s_add_i32 s72, 0, 0x21a00
	s_add_i32 s73, 0, 0x20800
	s_movk_i32 s74, 0x880
	v_mov_b32_e32 v109, 0x358637bd
	s_mov_b32 s75, 0x800000
	s_mov_b64 s[48:49], 0x100000
	s_mov_b64 s[50:51], 0x40000
	v_xor_b32_e32 v110, 32, v106
	s_branch .LBB0_594

; __device__ __forceinline__ unsigned xb_add(unsigned* p, unsigned v) { return __hip_atomic_fetch_add(p, v, __ATOMIC_RELAXED, __HIP_MEMORY_SCOPE_AGENT); }
; __device__ __forceinline__ void xcd_barrier(const XcdBarrier& b) {
;   asm volatile("s_waitcnt vmcnt(0)" ::: "memory");
;   __syncthreads();
;   if (threadIdx.x == 0) {
;     unsigned* bar = b.bar;
;     __builtin_amdgcn_s_waitcnt(0);
;     const unsigned old = xb_add(&bar[XB_XSUB(b.x)], 1u);
;     const unsigned gen = old / b.nloc;
;     if (old + 1u == (gen + 1u) * b.nloc) {
;       __builtin_amdgcn_fence(__ATOMIC_RELEASE, "agent");
;       asm volatile("s_waitcnt vmcnt(0)" ::: "memory");
;       const unsigned og = xb_add(&bar[XB_TOP], 1u);
.LBB0_609:
	s_setprio 0
	s_waitcnt vmcnt(0)
	s_barrier
	s_mov_b64 s[2:3], exec
	v_readlane_b32 s4, v248, 8
	v_readlane_b32 s5, v248, 9
	s_and_b64 s[4:5], s[2:3], s[4:5]
	v_readlane_b32 s36, v247, 0
	v_readlane_b32 s37, v248, 61
	s_mov_b64 exec, s[4:5]
	s_cbranch_execz .LBB0_646
	s_mov_b64 s[4:5], exec
	v_mbcnt_lo_u32_b32 v0, s4, 0
	v_readlane_b32 s6, v248, 26
	v_mbcnt_hi_u32_b32 v0, s5, v0
	s_lshl_b32 s22, s6, 6
	s_mov_b32 s9, 0
	v_cmp_eq_u32_e32 vcc, 0, v0
	s_waitcnt vmcnt(0) expcnt(0) lgkmcnt(0)
	s_and_saveexec_b64 s[6:7], vcc
	s_cbranch_execz .LBB0_612
	s_add_i32 s8, s22, 0x500
	s_lshl_b64 s[8:9], s[8:9], 2
	v_readlane_b32 s10, v248, 6
	v_readlane_b32 s11, v248, 7
	s_add_u32 s8, s10, s8
	s_addc_u32 s9, s11, s9
	s_bcnt1_i32_b64 s4, s[4:5]
	v_mov_b32_e32 v1, 0
	v_mov_b32_e32 v2, s4
	global_atomic_add v1, v1, v2, s[8:9] sc0
